# LayerNorm wave reductions: xor-16/xor-32 steps via v_permlane16_swap / v_permlane32_swap (no LDS round trips left in the reduction)
# speedup vs baseline: 1.0112x; 1.0047x over previous
; __device__ __forceinline__ float wave_sum(float v) {
; #pragma unroll
;     for (int o = 1; o < 64; o <<= 1) v += __shfl_xor(v, o);
;     return v;
; }
; __global__ void __launch_bounds__(512, 2) mk_fwd(Args args) {
;     ...
;                     float s = 0.f;
; #pragma unroll
;                     for (int j = 0; j < 4; ++j) s += (v[j][0] + v[j][1]) + (v[j][2] + v[j][3]);
;                     const float mean = wave_sum(s) * (1.0f / DM); float s2 = 0.f;
; #pragma unroll
;                     for (int j = 0; j < 4; ++j) { v[j] = v[j] - mean; s2 += (v[j][0] * v[j][0] + v[j][1] * v[j][1]) + (v[j][2] * v[j][2] + v[j][3] * v[j][3]); }
;                     const float rstd = 1.0f / sqrtf(wave_sum(s2) * (1.0f / DM) + LN_EPS);
;                     if (lane == 0) { STAT[2 * (size_t)row] = mean; STAT[2 * (size_t)row + 1] = rstd; }
.LBB0_822:
	s_waitcnt vmcnt(0) lgkmcnt(0)
	v_mov_b32_e32 v56, v31
	v_mov_b32_e32 v57, v32
	v_mov_b32_e32 v58, v30
	v_mov_b32_e32 v59, v33
	v_pk_add_f32 v[56:57], v[56:57], v[58:59]
	v_mov_b32_e32 v58, v27
	v_mov_b32_e32 v59, v28
	v_mov_b32_e32 v62, v26
	v_mov_b32_e32 v63, v29
	v_pk_add_f32 v[58:59], v[58:59], v[62:63]
	v_add_f32_e32 v56, v56, v57
	v_pk_add_f32 v[58:59], v[58:59], v[58:59] op_sel_hi:[0,1]
	v_add_f32_e32 v57, 0, v56
	v_add_f32_e32 v63, v22, v23
	v_add_f32_e32 v65, v24, v25
	v_mov_b32_e32 v62, v18
	v_mov_b32_e32 v64, v19
	v_mov_b32_e32 v58, v20
	v_mov_b32_e32 v56, v21
	v_pk_add_f32 v[62:63], v[62:63], v[64:65]
	v_pk_add_f32 v[56:57], v[58:59], v[56:57]
	s_nop 0
	v_pk_add_f32 v[56:57], v[62:63], v[56:57]
	s_nop 0
	v_add_f32_e32 v56, v56, v57
	s_nop 1
	v_add_f32_dpp v56, v56, v56 quad_perm:[1,0,3,2] row_mask:0xf bank_mask:0xf
	s_nop 1
	v_add_f32_dpp v56, v56, v56 quad_perm:[2,3,0,1] row_mask:0xf bank_mask:0xf
	s_nop 1
	v_add_f32_dpp v56, v56, v56 row_half_mirror row_mask:0xf bank_mask:0xf
	s_nop 1
	v_add_f32_dpp v56, v56, v56 row_mirror row_mask:0xf bank_mask:0xf
	v_mov_b32_e32 v57, v56
	s_nop 1
	v_permlane16_swap_b32_e32 v57, v56
	v_add_f32_e32 v56, v56, v57
	v_mov_b32_e32 v57, v56
	s_nop 1
	v_permlane32_swap_b32_e32 v57, v56
	v_add_f32_e32 v57, v56, v57
	v_fmamk_f32 v33, v57, 0xba800000, v33
	v_fmamk_f32 v31, v57, 0xba800000, v31
	v_fmamk_f32 v32, v57, 0xba800000, v32
	v_fmac_f32_e32 v30, 0xba800000, v57
	v_mul_f32_e32 v56, v31, v31
	v_mul_f32_e32 v58, v33, v33
	v_fmamk_f32 v29, v57, 0xba800000, v29
	v_fmamk_f32 v27, v57, 0xba800000, v27
	v_fmac_f32_e32 v56, v30, v30
	v_fmac_f32_e32 v58, v32, v32
	v_fmamk_f32 v28, v57, 0xba800000, v28
	v_add_f32_e32 v56, v56, v58
	v_fmac_f32_e32 v26, 0xba800000, v57
	v_mul_f32_e32 v58, v27, v27
	v_mul_f32_e32 v59, v29, v29
	v_fmac_f32_e32 v58, v26, v26
	v_fmac_f32_e32 v59, v28, v28
	v_add_f32_e32 v58, v58, v59
	v_fmamk_f32 v25, v57, 0xba800000, v25
	v_fmamk_f32 v23, v57, 0xba800000, v23
	v_add_f32_e32 v56, v56, v58
	v_fmamk_f32 v24, v57, 0xba800000, v24
	v_fmac_f32_e32 v22, 0xba800000, v57
	v_mul_f32_e32 v58, v23, v23
	v_mul_f32_e32 v59, v25, v25
	v_fmac_f32_e32 v58, v22, v22
	v_fmac_f32_e32 v59, v24, v24
	v_add_f32_e32 v58, v58, v59
	v_fmamk_f32 v21, v57, 0xba800000, v21
	v_fmamk_f32 v19, v57, 0xba800000, v19
	v_add_f32_e32 v56, v58, v56
	v_fmamk_f32 v20, v57, 0xba800000, v20
	v_fmac_f32_e32 v18, 0xba800000, v57
	v_mul_f32_e32 v58, v19, v19
	v_mul_f32_e32 v59, v21, v21
	v_fmac_f32_e32 v58, v18, v18
	v_fmac_f32_e32 v59, v20, v20
	v_add_f32_e32 v58, v58, v59
	v_add_f32_e32 v56, v58, v56
	s_nop 1
	v_add_f32_dpp v56, v56, v56 quad_perm:[1,0,3,2] row_mask:0xf bank_mask:0xf
	s_nop 1
	v_add_f32_dpp v56, v56, v56 quad_perm:[2,3,0,1] row_mask:0xf bank_mask:0xf
	s_nop 1
	v_add_f32_dpp v56, v56, v56 row_half_mirror row_mask:0xf bank_mask:0xf
	s_nop 1
	v_add_f32_dpp v56, v56, v56 row_mirror row_mask:0xf bank_mask:0xf
	v_mov_b32_e32 v58, v56
	s_nop 1
	v_permlane16_swap_b32_e32 v58, v56
	v_add_f32_e32 v56, v56, v58
	v_mov_b32_e32 v58, v56
	s_nop 1
	v_permlane32_swap_b32_e32 v58, v56
	v_add_f32_e32 v56, v56, v58
	v_fmamk_f32 v56, v56, 0x3a800000, v228
	v_mul_f32_e32 v58, 0x4f800000, v56
	v_cmp_gt_f32_e32 vcc, s28, v56
	s_nop 1
	v_cndmask_b32_e32 v56, v56, v58, vcc
	v_sqrt_f32_e32 v58, v56
	s_nop 0
	v_add_u32_e32 v59, -1, v58
	v_fma_f32 v63, -v59, v58, v56
	v_add_u32_e32 v62, 1, v58
	v_cmp_ge_f32_e64 s[4:5], 0, v63
	s_nop 1
	v_cndmask_b32_e64 v59, v58, v59, s[4:5]
	v_fma_f32 v58, -v62, v58, v56
	v_cmp_lt_f32_e64 s[4:5], 0, v58
	s_nop 1
	v_cndmask_b32_e64 v58, v59, v62, s[4:5]
	v_mul_f32_e32 v59, 0x37800000, v58
	v_cndmask_b32_e32 v58, v58, v59, vcc
	v_cmp_class_f32_e32 vcc, v56, v238
	s_nop 1
	v_cndmask_b32_e32 v56, v58, v56, vcc
	v_div_scale_f32 v58, s[4:5], v56, v56, 1.0
	v_rcp_f32_e32 v59, v58
	s_nop 0
	v_fma_f32 v62, -v58, v59, 1.0
	v_fmac_f32_e32 v59, v62, v59
	v_div_scale_f32 v62, vcc, 1.0, v56, 1.0
	v_mul_f32_e32 v63, v62, v59
	v_fma_f32 v64, -v58, v63, v62
	v_fmac_f32_e32 v63, v64, v59
	v_fma_f32 v58, -v58, v63, v62
	v_div_fmas_f32 v58, v58, v59, v63
	v_div_fixup_f32 v56, v58, v56, 1.0
	s_and_saveexec_b64 s[4:5], s[0:1]
	s_cbranch_execz .LBB0_824
	v_readlane_b32 s18, v254, 36
	v_readlane_b32 s19, v254, 37
	s_add_u32 s18, s18, s15
	s_addc_u32 s19, s19, s16
	v_mul_f32_e32 v58, 0x3a800000, v57
	v_mov_b32_e32 v59, v56
	v_mov_b64_e32 v[62:63], s[18:19]
	global_store_dwordx2 v[62:63], v[58:59], off

; __device__ __forceinline__ float wave_sum(float v) {
; #pragma unroll
;     for (int o = 1; o < 64; o <<= 1) v += __shfl_xor(v, o);
;     return v;
; }
; __global__ void __launch_bounds__(512, 2) mk_fwd(Args args) {
;     ...
;                     float s = 0.f;
; #pragma unroll
;                     for (int j = 0; j < 4; ++j) s += (v[j][0] + v[j][1]) + (v[j][2] + v[j][3]);
;                     const float mean = wave_sum(s) * (1.0f / DM); float s2 = 0.f;
; #pragma unroll
;                     for (int j = 0; j < 4; ++j) { v[j] = v[j] - mean; s2 += (v[j][0] * v[j][0] + v[j][1] * v[j][1]) + (v[j][2] * v[j][2] + v[j][3] * v[j][3]); }
;                     const float rstd = 1.0f / sqrtf(wave_sum(s2) * (1.0f / DM) + LN_EPS);
;                     if (lane == 0) { STAT[2 * (size_t)row] = mean; STAT[2 * (size_t)row + 1] = rstd; }
.LBB0_841:
	v_mov_b32_e32 v18, v11
	v_mov_b32_e32 v19, v12
	v_mov_b32_e32 v20, v10
	v_mov_b32_e32 v21, v13
	v_pk_add_f32 v[18:19], v[18:19], v[20:21]
	v_mov_b32_e32 v20, v7
	v_mov_b32_e32 v21, v8
	v_mov_b32_e32 v22, v6
	v_mov_b32_e32 v23, v9
	v_pk_add_f32 v[20:21], v[20:21], v[22:23]
	v_add_f32_e32 v18, v18, v19
	v_pk_add_f32 v[20:21], v[20:21], v[20:21] op_sel_hi:[0,1]
	v_add_f32_e32 v19, 0, v18
	v_add_f32_e32 v23, v2, v3
	v_add_f32_e32 v25, v4, v5
	v_mov_b32_e32 v22, v14
	v_mov_b32_e32 v24, v15
	v_mov_b32_e32 v20, v16
	v_mov_b32_e32 v18, v17
	v_pk_add_f32 v[14:15], v[22:23], v[24:25]
	v_pk_add_f32 v[16:17], v[20:21], v[18:19]
	s_ashr_i32 s91, s90, 31
	v_pk_add_f32 v[14:15], v[14:15], v[16:17]
	s_nop 0
	v_add_f32_e32 v14, v14, v15
	s_nop 1
	v_add_f32_dpp v14, v14, v14 quad_perm:[1,0,3,2] row_mask:0xf bank_mask:0xf
	s_nop 1
	v_add_f32_dpp v14, v14, v14 quad_perm:[2,3,0,1] row_mask:0xf bank_mask:0xf
	s_nop 1
	v_add_f32_dpp v14, v14, v14 row_half_mirror row_mask:0xf bank_mask:0xf
	s_nop 1
	v_add_f32_dpp v14, v14, v14 row_mirror row_mask:0xf bank_mask:0xf
	v_mov_b32_e32 v15, v14
	s_nop 1
	v_permlane16_swap_b32_e32 v15, v14
	v_add_f32_e32 v14, v14, v15
	v_mov_b32_e32 v15, v14
	s_nop 1
	v_permlane32_swap_b32_e32 v15, v14
	v_add_f32_e32 v15, v14, v15
	v_fmac_f32_e32 v13, 0xba800000, v15
	v_fmac_f32_e32 v11, 0xba800000, v15
	v_fmac_f32_e32 v12, 0xba800000, v15
	v_fmac_f32_e32 v10, 0xba800000, v15
	v_mul_f32_e32 v14, v11, v11
	v_mul_f32_e32 v16, v13, v13
	v_fmac_f32_e32 v9, 0xba800000, v15
	v_fmac_f32_e32 v7, 0xba800000, v15
	v_fmac_f32_e32 v14, v10, v10
	v_fmac_f32_e32 v16, v12, v12
	v_fmac_f32_e32 v8, 0xba800000, v15
	v_add_f32_e32 v14, v14, v16
	v_fmac_f32_e32 v6, 0xba800000, v15
	v_mul_f32_e32 v16, v7, v7
	v_mul_f32_e32 v17, v9, v9
	v_fmac_f32_e32 v16, v6, v6
	v_fmac_f32_e32 v17, v8, v8
	v_add_f32_e32 v16, v16, v17
	v_fmac_f32_e32 v5, 0xba800000, v15
	v_fmac_f32_e32 v3, 0xba800000, v15
	v_add_f32_e32 v14, v14, v16
	v_fmac_f32_e32 v4, 0xba800000, v15
	v_fmac_f32_e32 v2, 0xba800000, v15
	v_mul_f32_e32 v16, v3, v3
	v_mul_f32_e32 v17, v5, v5
	v_fmac_f32_e32 v16, v2, v2
	v_fmac_f32_e32 v17, v4, v4
	v_add_f32_e32 v16, v16, v17
	v_fmac_f32_e32 v53, 0xba800000, v15
	v_fmac_f32_e32 v55, 0xba800000, v15
	v_add_f32_e32 v14, v16, v14
	v_fmac_f32_e32 v52, 0xba800000, v15
	v_fmac_f32_e32 v54, 0xba800000, v15
	v_mul_f32_e32 v16, v55, v55
	v_mul_f32_e32 v17, v53, v53
	v_fmac_f32_e32 v16, v54, v54
	v_fmac_f32_e32 v17, v52, v52
	v_add_f32_e32 v16, v16, v17
	v_add_f32_e32 v14, v16, v14
	s_nop 1
	v_add_f32_dpp v14, v14, v14 quad_perm:[1,0,3,2] row_mask:0xf bank_mask:0xf
	s_nop 1
	v_add_f32_dpp v14, v14, v14 quad_perm:[2,3,0,1] row_mask:0xf bank_mask:0xf
	s_nop 1
	v_add_f32_dpp v14, v14, v14 row_half_mirror row_mask:0xf bank_mask:0xf
	s_nop 1
	v_add_f32_dpp v14, v14, v14 row_mirror row_mask:0xf bank_mask:0xf
	v_mov_b32_e32 v16, v14
	s_nop 1
	v_permlane16_swap_b32_e32 v16, v14
	v_add_f32_e32 v14, v14, v16
	v_mov_b32_e32 v16, v14
	s_nop 1
	v_permlane32_swap_b32_e32 v16, v14
	v_add_f32_e32 v14, v14, v16
	v_fmamk_f32 v14, v14, 0x3a800000, v228
	v_mul_f32_e32 v16, 0x4f800000, v14
	v_cmp_gt_f32_e32 vcc, s28, v14
	s_nop 1
	v_cndmask_b32_e32 v14, v14, v16, vcc
	v_sqrt_f32_e32 v16, v14
	s_nop 0
	v_add_u32_e32 v17, -1, v16
	v_fma_f32 v19, -v17, v16, v14
	v_add_u32_e32 v18, 1, v16
	v_cmp_ge_f32_e64 s[4:5], 0, v19
	s_nop 1
	v_cndmask_b32_e64 v17, v16, v17, s[4:5]
	v_fma_f32 v16, -v18, v16, v14
	v_cmp_lt_f32_e64 s[4:5], 0, v16
	s_nop 1
	v_cndmask_b32_e64 v16, v17, v18, s[4:5]
	v_mul_f32_e32 v17, 0x37800000, v16
	v_cndmask_b32_e32 v16, v16, v17, vcc
	v_cmp_class_f32_e32 vcc, v14, v238
	s_nop 1
	v_cndmask_b32_e32 v14, v16, v14, vcc
	v_div_scale_f32 v16, s[4:5], v14, v14, 1.0
	v_rcp_f32_e32 v17, v16
	s_nop 0
	v_fma_f32 v18, -v16, v17, 1.0
	v_fmac_f32_e32 v17, v18, v17
	v_div_scale_f32 v18, vcc, 1.0, v14, 1.0
	v_mul_f32_e32 v19, v18, v17
	v_fma_f32 v20, -v16, v19, v18
	v_fmac_f32_e32 v19, v20, v17
	v_fma_f32 v16, -v16, v19, v18
	v_div_fmas_f32 v16, v16, v17, v19
	v_div_fixup_f32 v14, v16, v14, 1.0
	s_and_saveexec_b64 s[4:5], s[0:1]
	s_cbranch_execz .LBB0_843
	s_lshl_b64 s[18:19], s[90:91], 3
	s_add_u32 s18, s42, s18
	s_addc_u32 s19, s43, s19
	v_mul_f32_e32 v16, 0x3a800000, v15
	v_mov_b32_e32 v17, v14
	v_mov_b64_e32 v[18:19], s[18:19]
	global_store_dwordx2 v[18:19], v[16:17], off
